# v20 + static s_setprio 1 for waves 4-7 during the attention phase (reset to 0 after)
# speedup vs baseline: 1.0013x; 1.0013x over previous
; #define ARGP(i) ka_ptr(ka, (i) * 8)
; #define ARG_WS() ((unsigned char*)ka_ptr(ka, 176))
; #define GET_LANE() int lane; asm volatile("v_mbcnt_lo_u32_b32 %0, -1, 0\n\tv_mbcnt_hi_u32_b32 %0, -1, %0" : "=v"(lane)); const int tid = wave * 64 + lane; (void)tid;
; template <int MODE, bool FIX> ...
;     const int r32 = lane & 31, hi = lane >> 5;
;     const int b = unit >> 7, rem = unit & 127;
;     int head, qtok, qcol, kcol, vcol, ocol, NTL, lrow0;
;     int s_sub = 0, tl0 = 0;
;     int qrow = 0, qc = 0, kc0 = 0, kr_lo = 0, wa_lo = 0, wa_hi = 0, rs = 0;
;     unsigned colmask = 0u;
;     if (MODE == 0) {
;         const int qblk = rem >> 1, kvh = rem & 1, q0 = qblk * 64;
;         head = kvh * 4 + (wid >> 1); s_sub = wid & 1; qtok = q0 + 32 * s_sub + r32; qcol = head * 64; kcol = 512 + kvh * 64; vcol = 640 + kvh * 64; ocol = head * 64;
;         tl0 = (2 - qblk) > 0 ? (2 - qblk) : 0; const int tl1 = (65 - qblk) < 4 ? (65 - qblk) : 4; NTL = tl1 - tl0 + 1; lrow0 = b * SEQ + q0 - 128 + 64 * tl0;
; __global__ void __launch_bounds__(NWAVES * 64, 2) fwd_kernel(Args args_unused) {
;     ...
;     if (IN(3)) for (int rep = 0; rep < NREP(3); ++rep) {
;         GET_LANE();
;         unsigned char* const ws = ARG_WS();
;         const bf16_t* QKV = (const bf16_t*)(ws + WS_QKV); bf16_t* Ob = (bf16_t*)(ws + WS_O); float* ssq1 = (float*)(ws + (FIRST_OF_2(3) ? WS_DUMMY : WS_SSQ1));
;         const float* sinkp = ARGP(I_SINK); const float* rpbp = ARGP(I_RPB);
;         const int per = (1024 + G - 1) / G;
;         const float MA = ((const float*)(ws + WS_BOUNDS))[0], MB = ((const float*)(ws + WS_BOUNDS))[1];
;         const bool fixA = MA < 48.0f, fixB = MB < 48.0f;
;         for (int i = 0; i < per; ++i) { const int ua = vcu2 * per + i; if (ua < 1024) { if (fixA) att::attn_unit<0, true>(lds, QKV, Ob, ssq1, sinkp, rpbp, ua, tid, lane, wave, MA); else att::attn_unit<0, false>(lds, QKV, Ob, ssq1, sinkp, rpbp, ua, tid, lane, wave, 0.f); } }
.LBB0_568:
	s_cmp_lt_i32 s89, 4
	v_writelane_b32 v255, s94, 2
	s_cselect_b64 s[0:1], -1, 0
	v_writelane_b32 v255, s0, 3
	s_nop 1
	v_writelane_b32 v255, s1, 4
	s_and_b64 s[0:1], s[0:1], s[4:5]
	s_andn2_b64 vcc, exec, s[0:1]
	s_cbranch_vccnz .LBB0_735
	s_abs_i32 s0, s33
	v_cvt_f32_u32_e32 v0, s0
	v_mbcnt_lo_u32_b32 v197, -1, 0
	v_mbcnt_hi_u32_b32 v197, -1, v197
	s_load_dwordx2 s[2:3], s[96:97], 0xb0
	s_waitcnt lgkmcnt(0)
	s_load_dwordx2 s[4:5], s[96:97], 0x50
	s_waitcnt lgkmcnt(0)
	v_rcp_iflag_f32_e32 v0, v0
	v_writelane_b32 v255, s4, 5
	s_load_dwordx2 s[6:7], s[96:97], 0x68
	s_waitcnt lgkmcnt(0)
	s_add_i32 s1, s33, 0x3ff
	v_mul_f32_e32 v0, 0x4f7ffffe, v0
	v_cvt_u32_f32_e32 v0, v0
	v_writelane_b32 v255, s5, 6
	v_writelane_b32 v255, s6, 7
	s_sub_i32 s5, 0, s0
	s_xor_b32 s4, s1, s33
	v_writelane_b32 v255, s7, 8
	v_readfirstlane_b32 s6, v0
	s_mul_i32 s5, s5, s6
	s_mul_hi_u32 s5, s6, s5
	s_abs_i32 s1, s1
	s_add_i32 s6, s6, s5
	s_mul_hi_u32 s5, s1, s6
	s_mul_i32 s6, s5, s0
	s_sub_i32 s1, s1, s6
	s_ashr_i32 s4, s4, 31
	s_add_i32 s6, s5, 1
	s_sub_i32 s7, s1, s0
	s_cmp_ge_u32 s1, s0
	s_cselect_b32 s5, s6, s5
	s_cselect_b32 s1, s7, s1
	s_add_i32 s6, s5, 1
	s_cmp_ge_u32 s1, s0
	s_cselect_b32 s0, s6, s5
	s_xor_b32 s0, s0, s4
	s_sub_i32 s94, s0, s4
	s_cmp_lt_i32 s94, 1
	s_mov_b32 s87, 0
	s_cbranch_scc1 .LBB0_735
	v_mov_b32_e32 v0, 0xc3000
	global_load_dwordx2 v[182:183], v0, s[2:3]
	v_writelane_b32 v255, s56, 0
	v_writelane_b32 v255, s92, 9
	v_add_u32_e32 v188, s71, v197
	v_and_b32_e32 v0, 7, v197
	v_writelane_b32 v255, s93, 10
	v_writelane_b32 v255, s83, 11
	v_writelane_b32 v255, s82, 12
	v_writelane_b32 v255, s90, 13
	v_writelane_b32 v255, s89, 14
	v_writelane_b32 v255, s96, 15
	s_movk_i32 s4, 0x90
	v_lshlrev_b32_e32 v1, 4, v197
	v_writelane_b32 v255, s97, 16
	v_ashrrev_i32_e32 v6, 3, v188
	v_readlane_b32 s0, v255, 2
	s_mul_i32 s0, s85, s0
	s_add_i32 s42, s60, s0
	v_lshlrev_b32_e32 v0, 4, v0
	v_writelane_b32 v255, s85, 1
	s_and_b64 s[0:1], s[18:19], exec
	v_mad_u64_u32 v[178:179], s[0:1], v6, s4, v[0:1]
	v_writelane_b32 v255, s71, 17
	v_ashrrev_i32_e32 v2, 5, v197
	s_cselect_b32 s1, s42, s64
	s_lshr_b32 s85, s95, 7
	s_bfe_u32 s74, s95, 0x10006
	s_cmp_ge_u32 s95, 0x100
	s_cbranch_scc0 .Lp3_prio_done
	s_setprio 1
.Lp3_prio_done:
	v_lshlrev_b32_e32 v3, 1, v197
	v_lshlrev_b32_e32 v198, 2, v2
	v_writelane_b32 v255, s95, 18
	s_add_u32 s0, s2, 0x6400000
	v_and_b32_e32 v196, 31, v197
	v_lshlrev_b32_e32 v176, 3, v2
	v_lshlrev_b32_e32 v189, 4, v2
	v_lshlrev_b32_e32 v190, 8, v2
	v_and_b32_e32 v191, 32, v3
	v_or_b32_e32 v2, 2, v198
	v_or_b32_e32 v3, 3, v198
	v_writelane_b32 v255, s1, 19
	s_mul_i32 s96, s94, s1
	s_addc_u32 s1, s3, 0
	s_movk_i32 s53, 0x1200
	v_cmp_gt_i32_e64 s[42:43], v2, v196
	v_cmp_gt_i32_e64 s[44:45], v3, v196
	v_cmp_lt_i32_e64 s[48:49], v2, v196
	v_cmp_lt_i32_e64 s[50:51], v3, v196
	s_add_u32 s78, s2, 0x10000000
	v_writelane_b32 v255, s0, 20
	s_addc_u32 s79, s3, 0
	s_mov_b32 s52, 0x42400000
	v_mov_b64_e32 v[2:3], s[0:1]
	v_writelane_b32 v255, s1, 21
	v_mad_i64_i32 v[2:3], s[0:1], v6, s53, v[2:3]
	s_add_u32 s0, s2, 0x40000
	s_addc_u32 s1, s3, 0
	v_writelane_b32 v255, s0, 22
	v_lshlrev_b32_e32 v5, 3, v197
	v_and_b32_e32 v7, 48, v1
	v_writelane_b32 v255, s1, 23
	v_and_b32_e32 v192, 24, v5
	v_lshlrev_b32_e32 v5, 6, v6
	v_and_b32_e32 v193, 0xc0, v1
	v_bfe_u32 v199, v197, 2, 2
	v_mov_b32_e32 v1, 0
	v_bfe_u32 v4, v197, 2, 1
	v_lshl_add_u64 v[180:181], v[2:3], 0, v[0:1]
	v_or_b32_e32 v0, v7, v5
	v_lshlrev_b32_e32 v195, 6, v199
	v_subrev_u32_e32 v16, 24, v196
	v_add_u32_e32 v8, -8, v196
	v_add_u32_e32 v9, -9, v196
	v_add_u32_e32 v10, -10, v196
	v_add_u32_e32 v11, -11, v196
	v_add_u32_e32 v12, -16, v196
	v_subrev_u32_e32 v13, 17, v196
	v_subrev_u32_e32 v14, 18, v196
	v_subrev_u32_e32 v15, 19, v196
	v_subrev_u32_e32 v17, 25, v196
	s_waitcnt vmcnt(0)
; template <int MODE, bool FIX> ...
;     ...
;     float m = FIX ? Mb : -INFINITY, l = 0.f;
;     const float ci = FIX ? -Mb : 0.f;
;     const f32x16 cinit = {ci, ci, ci, ci, ci, ci, ci, ci, ci, ci, ci, ci, ci, ci, ci, ci};
;     ...
;             ATT_STEP_PRE(i)
;             if (MODE == 0) {
;                 const int tl = ATT_SEQ_TL(i); const int dA = 2 * tl - s_sub, dB = dA + 1;
;                 const int a0 = (dA < 0 || dA > 8) ? 99 : (dA == 0 ? 0 : -99), b0 = (dA < 0 || dA > 8) ? -99 : (dA == 8 ? 0 : 99);
;                 const int a1 = (dB < 0 || dB > 8) ? 99 : (dB == 0 ? 0 : -99), b1 = (dB < 0 || dB > 8) ? -99 : (dB == 8 ? 0 : 99);
;                 tile64<true>(buf, qf, o0, o1, l, lane, r32, hi, cinit, a0, b0, a1, b1);
	v_cmp_ngt_f32_e64 s[0:1], s52, v182
	v_subrev_u32_e32 v18, 26, v196
	v_subrev_u32_e32 v19, 27, v196
	v_writelane_b32 v255, s0, 24
	v_cmp_gt_i32_e64 s[24:25], v198, v16
	v_or_b32_e32 v20, 1, v198
	v_writelane_b32 v255, s1, 25
	v_cmp_gt_u32_e64 s[0:1], 32, v197
	v_cmp_lt_i32_e64 s[62:63], v198, v16
	v_mul_u32_u24_e32 v179, 0x90, v196
	v_writelane_b32 v255, s0, 26
	v_xor_b32_e32 v16, 0x80000000, v182
	v_sub_u32_e32 v201, v198, v196
	v_writelane_b32 v255, s1, 27
	s_movk_i32 s0, 0x1040
	v_mad_u32_u24 v194, v4, s0, v0
	v_or_b32_e32 v0, v190, v195
	s_sub_i32 s1, 0, s74
	v_or3_b32 v0, v0, v191, v192
	v_writelane_b32 v255, s1, 28
	v_add_u32_e32 v217, 0, v0
	v_mad_u32_u24 v0, v4, s0, v5
	v_or_b32_e32 v0, v0, v7
	v_writelane_b32 v255, s78, 29
	v_add_u32_e32 v0, 0, v0
	v_ashrrev_i32_e32 v177, 31, v176
	v_writelane_b32 v255, s79, 30
	v_cmp_gt_i32_e64 s[4:5], v198, v196
	v_cmp_lt_i32_e64 s[6:7], v198, v196
	v_cmp_gt_i32_e64 s[8:9], v198, v8
	v_cmp_gt_i32_e64 s[10:11], v198, v9
	v_cmp_gt_i32_e64 s[12:13], v198, v10
	v_cmp_gt_i32_e64 s[14:15], v198, v11
	v_cmp_gt_i32_e64 s[16:17], v198, v12
	v_cmp_gt_i32_e64 s[18:19], v198, v13
	v_cmp_gt_i32_e64 s[20:21], v198, v14
	v_cmp_gt_i32_e64 s[22:23], v198, v15
	v_cmp_gt_i32_e64 s[26:27], v198, v17
	v_cmp_gt_i32_e64 s[28:29], v198, v18
	v_cmp_gt_i32_e64 s[30:31], v198, v19
	v_cmp_lt_i32_e64 s[34:35], v198, v8
	v_cmp_lt_i32_e64 s[36:37], v198, v9
	v_cmp_lt_i32_e64 s[38:39], v198, v10
	v_cmp_lt_i32_e64 s[40:41], v198, v11
	v_cmp_lt_i32_e64 s[46:47], v20, v196
	v_lshl_or_b32 v242, s74, 5, v196
	v_cmp_lt_i32_e64 s[54:55], v198, v12
	v_cmp_lt_i32_e64 s[56:57], v198, v13
	v_cmp_lt_i32_e64 s[58:59], v198, v14
	v_cmp_lt_i32_e64 s[60:61], v198, v15
	v_cmp_lt_i32_e64 s[64:65], v198, v17
	v_cmp_lt_i32_e64 s[66:67], v198, v18
	v_cmp_lt_i32_e64 s[68:69], v198, v19
	v_mov_b32_e32 v17, v16
	v_mov_b32_e32 v18, v16
	v_mov_b32_e32 v19, v16
	v_mov_b32_e32 v20, v16
	v_mov_b32_e32 v21, v16
	v_mov_b32_e32 v22, v16
	v_mov_b32_e32 v23, v16
	v_mov_b32_e32 v24, v16
	v_mov_b32_e32 v25, v16
	v_mov_b32_e32 v26, v16
	v_mov_b32_e32 v27, v16
	v_mov_b32_e32 v28, v16
	v_mov_b32_e32 v29, v16
	v_mov_b32_e32 v30, v16
	v_mov_b32_e32 v31, v16
	v_add_u32_e32 v202, 1, v201
	v_add_u32_e32 v203, 2, v201
	v_add_u32_e32 v204, 3, v201
	v_add_u32_e32 v205, 8, v201
	v_add_u32_e32 v206, 9, v201
	v_add_u32_e32 v207, 10, v201
	v_add_u32_e32 v208, 11, v201
	v_add_u32_e32 v209, 16, v201
	v_add_u32_e32 v210, 17, v201
	v_add_u32_e32 v211, 18, v201
	v_add_u32_e32 v212, 19, v201
	v_add_u32_e32 v213, 24, v201
	v_add_u32_e32 v214, 25, v201
	v_add_u32_e32 v215, 26, v201
	v_add_u32_e32 v216, 27, v201
	v_add_u32_e32 v218, 0x2400, v0
	v_add3_u32 v219, v179, v189, 0
	v_add_u32_e32 v220, 0, v178
	s_mov_b32 s76, 0xff800000
	v_mov_b32_e32 v221, 0x1200
	v_mov_b32_e32 v222, 0xff800000
	v_mov_b32_e32 v223, 0x63
	v_mov_b32_e32 v224, 0xffffff9d
	s_mov_b32 s73, s96
	s_mov_b32 s95, 0
	v_writelane_b32 v255, s85, 31
	v_cmp_gt_i32_e32 vcc, 0, v201
	s_nop 1
	v_cndmask_b32_e32 v226, v16, v222, vcc
	v_cmp_gt_i32_e32 vcc, 0, v202
	s_nop 1
	v_cndmask_b32_e32 v227, v16, v222, vcc
	v_cmp_gt_i32_e32 vcc, 0, v203
	s_nop 1
	v_cndmask_b32_e32 v228, v16, v222, vcc
	v_cmp_gt_i32_e32 vcc, 0, v204
	s_nop 1
	v_cndmask_b32_e32 v229, v16, v222, vcc
	v_cmp_gt_i32_e32 vcc, 0, v205
	s_nop 1
	v_cndmask_b32_e32 v230, v16, v222, vcc
	v_cmp_gt_i32_e32 vcc, 0, v206
	s_nop 1
	v_cndmask_b32_e32 v231, v16, v222, vcc
	v_cmp_gt_i32_e32 vcc, 0, v207
	s_nop 1
	v_cndmask_b32_e32 v232, v16, v222, vcc
	v_cmp_gt_i32_e32 vcc, 0, v208
	s_nop 1
	v_cndmask_b32_e32 v233, v16, v222, vcc
	v_cmp_gt_i32_e32 vcc, 0, v209
	s_nop 1
	v_cndmask_b32_e32 v234, v16, v222, vcc
	v_cmp_gt_i32_e32 vcc, 0, v210
	s_nop 1
	v_cndmask_b32_e32 v235, v16, v222, vcc
	v_cmp_gt_i32_e32 vcc, 0, v211
	s_nop 1
	v_cndmask_b32_e32 v236, v16, v222, vcc
	v_cmp_gt_i32_e32 vcc, 0, v212
	s_nop 1
	v_cndmask_b32_e32 v237, v16, v222, vcc
	v_cmp_gt_i32_e32 vcc, 0, v213
	s_nop 1
	v_cndmask_b32_e32 v238, v16, v222, vcc
	v_cmp_gt_i32_e32 vcc, 0, v214
	s_nop 1
	v_cndmask_b32_e32 v239, v16, v222, vcc
	v_cmp_gt_i32_e32 vcc, 0, v215
	s_nop 1
	v_cndmask_b32_e32 v240, v16, v222, vcc
	v_cmp_gt_i32_e32 vcc, 0, v216
	s_nop 1
	v_cndmask_b32_e32 v241, v16, v222, vcc
	v_cmp_lt_i32_e32 vcc, 0, v201
	s_nop 1
	v_cndmask_b32_e32 v200, v16, v222, vcc
	v_cmp_lt_i32_e32 vcc, 0, v202
	s_nop 1
	v_cndmask_b32_e32 v201, v16, v222, vcc
	v_cmp_lt_i32_e32 vcc, 0, v203
	s_nop 1
	v_cndmask_b32_e32 v202, v16, v222, vcc
	v_cmp_lt_i32_e32 vcc, 0, v204
	s_nop 1
	v_cndmask_b32_e32 v203, v16, v222, vcc
	v_cmp_lt_i32_e32 vcc, 0, v205
	s_nop 1
	v_cndmask_b32_e32 v204, v16, v222, vcc
	v_cmp_lt_i32_e32 vcc, 0, v206
	s_nop 1
	v_cndmask_b32_e32 v205, v16, v222, vcc
	v_cmp_lt_i32_e32 vcc, 0, v207
	s_nop 1
	v_cndmask_b32_e32 v206, v16, v222, vcc
	v_cmp_lt_i32_e32 vcc, 0, v208
	s_nop 1
	v_cndmask_b32_e32 v207, v16, v222, vcc
	v_cmp_lt_i32_e32 vcc, 0, v209
	s_nop 1
	v_cndmask_b32_e32 v208, v16, v222, vcc
	v_cmp_lt_i32_e32 vcc, 0, v210
	s_nop 1
	v_cndmask_b32_e32 v209, v16, v222, vcc
	v_cmp_lt_i32_e32 vcc, 0, v211
	s_nop 1
	v_cndmask_b32_e32 v210, v16, v222, vcc
	v_cmp_lt_i32_e32 vcc, 0, v212
	s_nop 1
	v_cndmask_b32_e32 v211, v16, v222, vcc
	v_cmp_lt_i32_e32 vcc, 0, v213
	s_nop 1
	v_cndmask_b32_e32 v212, v16, v222, vcc
	v_cmp_lt_i32_e32 vcc, 0, v214
	s_nop 1
	v_cndmask_b32_e32 v213, v16, v222, vcc
	v_cmp_lt_i32_e32 vcc, 0, v215
	s_nop 1
	v_cndmask_b32_e32 v214, v16, v222, vcc
	v_cmp_lt_i32_e32 vcc, 0, v216
	s_nop 1
	v_cndmask_b32_e32 v215, v16, v222, vcc
	s_branch .LBB0_573

; #define LAS __attribute__((address_space(3)))
; __device__ __forceinline__ unsigned xb_ld(unsigned* p)              { return __hip_atomic_load(p, __ATOMIC_RELAXED, __HIP_MEMORY_SCOPE_AGENT); }
; __device__ __forceinline__ void xcd_barrier_complete(unsigned* bar, unsigned x, unsigned G, unsigned& nloc, unsigned& nx) {
;     unsigned sum, cnt, mine, sp = 0u;
;     for (;;) {
;         sum = 0u; cnt = 0u; mine = 0u;
; #pragma unroll
;         for (unsigned j = 0; j < 16; ++j) { const unsigned c = xb_ld(&bar[XB_XCNT(j)]); sum += c; cnt += (c > 0u) ? 1u : 0u; mine = (j == x) ? c : mine; }
;         if (sum == G) break;
;         __builtin_amdgcn_s_sleep(1);
;         if ((++sp & 255u) == 0u) { if (xb_ld(&bar[XB_TMO])) break; if (sp > XB_SPIN_CAP) { atomicAdd(&bar[XB_TMO], 1u); break; } }
;     }
; __device__ __forceinline__ void xcd_barrier(unsigned* bar, unsigned x, volatile LAS unsigned* st, unsigned G, int tid) {
;     asm volatile("s_waitcnt vmcnt(0)" ::: "memory");
;     __syncthreads();
;     if (tid == 0) {
;         __builtin_amdgcn_s_waitcnt(0);
;         unsigned nloc = st[0], nx = st[1];
;         if (nloc == 0u) { xcd_barrier_complete(bar, x, G, nloc, nx); st[0] = nloc; st[1] = nx; }
.LBB0_735:
	s_setprio 0
	s_cmp_gt_i32 s83, 4
	v_readlane_b32 s0, v255, 3
	s_cselect_b64 s[4:5], -1, 0
	v_readlane_b32 s1, v255, 4
	s_and_b64 s[0:1], s[0:1], s[4:5]
	s_andn2_b64 vcc, exec, s[0:1]
	v_readlane_b32 s94, v255, 2
	s_cbranch_vccnz .LBB0_814
	v_mbcnt_lo_u32_b32 v0, -1, 0
	v_mbcnt_hi_u32_b32 v0, -1, v0
	s_mov_b64 s[6:7], -1
	v_add_u32_e32 v2, s71, v0
	s_and_b64 vcc, exec, s[92:93]
	v_cmp_eq_u32_e64 s[2:3], 0, v2
	s_cbranch_vccz .LBB0_790
	s_load_dwordx2 s[8:9], s[96:97], 0xb0
	s_waitcnt lgkmcnt(0)
	s_waitcnt vmcnt(0)
	s_waitcnt lgkmcnt(0)
	s_barrier
	s_and_saveexec_b64 s[6:7], s[2:3]
	s_cbranch_execz .LBB0_789
	s_add_i32 s0, 0, 0x22000
	v_mov_b32_e32 v0, s0
	s_waitcnt vmcnt(0) expcnt(0) lgkmcnt(0)
	ds_read_b32 v3, v0
	s_add_i32 s0, 0, 0x22004
	v_mov_b32_e32 v0, s0
	ds_read_b32 v0, v0
	s_waitcnt lgkmcnt(1)
	v_cmp_ne_u32_e32 vcc, 0, v3
	s_cbranch_vccnz .LBB0_753
	s_add_u32 s2, s8, 0xa0200
	s_addc_u32 s3, s9, 0
	s_add_u32 s10, s8, 0xa0400
	s_addc_u32 s11, s9, 0
	s_add_u32 s12, s8, 0xa0500
	s_addc_u32 s13, s9, 0
	s_add_u32 s14, s8, 0xa0600
	s_addc_u32 s15, s9, 0
	s_add_u32 s16, s8, 0xa0700
	s_addc_u32 s17, s9, 0
	s_add_u32 s18, s8, 0xa0800
	s_addc_u32 s19, s9, 0
	s_add_u32 s20, s8, 0xa0900
	s_addc_u32 s21, s9, 0
	s_add_u32 s22, s8, 0xa0a00
	s_addc_u32 s23, s9, 0
	s_add_u32 s24, s8, 0xa0b00
	s_addc_u32 s25, s9, 0
	s_add_u32 s26, s8, 0xa0c00
	s_addc_u32 s27, s9, 0
	s_add_u32 s28, s8, 0xa0d00
	s_addc_u32 s29, s9, 0
	s_add_u32 s30, s8, 0xa0e00
	s_addc_u32 s31, s9, 0
	s_add_u32 s34, s8, 0xa0f00
	s_addc_u32 s35, s9, 0
	s_add_u32 s36, s8, 0xa1000
	s_addc_u32 s37, s9, 0
	s_add_u32 s38, s8, 0xa1100
	s_addc_u32 s39, s9, 0
	s_add_u32 s40, s8, 0xa1200
	s_addc_u32 s41, s9, 0
	s_add_u32 s42, s8, 0xa1300
	s_addc_u32 s43, s9, 0
	s_mov_b32 s0, 1
	v_mov_b32_e32 v17, 0
	s_branch .LBB0_741
